# attention units of blocks 32..255 pulled in pairs from a device counter (prefetched one unit ahead), conversion units stay static
# baseline (speedup 1.0000x reference)
; DI void phase_m2(const Params& p, int l, int bid, int nb, h16* lds) {
;     ...
;   const int ustart = (bid < 32) ? bid : bid;
;   const int ustep = (bid < 32) ? total : (nb - 32);
;   for (int u = ustart; u < total; u += ustep) {
;     int v = u;
;     if (v >= 5288) { v -= 5288; if (v < nA) conv_one(p, l, 2560 + v, lds); else conv_one(p, l + 1, v - nA, lds); continue; }
.LBB0_892:
	s_and_b64 s[2:3], exec, s[2:3]
	s_movk_i32 s2, 0x2700
	s_cselect_b32 s91, s2, 0x5880
	v_readlane_b32 s2, v255, 30
	v_readlane_b32 s4, v255, 32
	v_readlane_b32 s3, v255, 31
	s_add_i32 s2, s4, 1
	v_readlane_b32 s5, v255, 33
	v_writelane_b32 v255, s2, 30
	s_cmp_lg_u32 s4, 3
	s_nop 0
	v_writelane_b32 v255, s3, 31
	s_cselect_b64 s[2:3], -1, 0
	v_writelane_b32 v255, s2, 36
	s_cmp_eq_u32 s4, 3
	s_nop 0
	v_writelane_b32 v255, s3, 37
	s_movk_i32 s2, 0xaa8
	s_cselect_b32 s2, s2, 0x14a8
	s_add_i32 s90, s91, s2
	v_cmp_gt_i32_e32 vcc, s90, v1
	s_and_saveexec_b64 s[64:65], vcc
	s_cbranch_execz .LBB0_1028
	v_readlane_b32 s16, v255, 32
	v_readlane_b32 s68, v255, 30
	v_readlane_b32 s2, v254, 31
	v_readlane_b32 s17, v255, 33
	v_readlane_b32 s69, v255, 31
	v_mov_b32_e32 v2, s2
	s_lshr_b32 s2, s68, 1
	s_mov_b32 s17, s69
	s_lshr_b32 s4, s16, 1
	v_readlane_b32 s36, v252, 11
	s_addk_i32 s91, 0xf600
	s_lshl_b32 s92, s16, 3
	s_mul_hi_u32 s6, s68, 0x2420000
	s_mul_i32 s7, s68, 0x2420000
	s_mul_i32 s66, s2, 0xb00000
	s_lshl_b32 s93, s2, 3
	s_lshl_b64 s[2:3], s[68:69], 22
	s_lshl_b32 s94, s4, 3
	s_mul_i32 s68, s4, 0xb00000
	s_lshl_b64 s[4:5], s[16:17], 22
	v_readlane_b32 s38, v252, 13
	v_readlane_b32 s48, v252, 23
	v_readlane_b32 s49, v252, 24
	v_readlane_b32 s50, v252, 25
	v_readlane_b32 s51, v252, 26
	v_readlane_b32 s39, v252, 14
	s_add_u32 s70, s38, s7
	v_readlane_b32 s48, v252, 43
	v_readlane_b32 s40, v252, 15
	v_readlane_b32 s41, v252, 16
	v_readlane_b32 s42, v252, 17
	v_readlane_b32 s43, v252, 18
	v_readlane_b32 s44, v252, 19
	v_readlane_b32 s45, v252, 20
	v_readlane_b32 s46, v252, 21
	v_readlane_b32 s47, v252, 22
	s_addc_u32 s71, s39, s6
	v_readlane_b32 s49, v252, 44
	v_readlane_b32 s50, v252, 45
	v_readlane_b32 s51, v252, 46
	v_readlane_b32 s52, v252, 47
	v_readlane_b32 s53, v252, 48
	v_readlane_b32 s54, v252, 49
	v_readlane_b32 s55, v252, 50
	v_readlane_b32 s56, v252, 51
	v_readlane_b32 s57, v252, 52
	s_add_u32 s72, s56, s66
	v_readlane_b32 s40, v252, 27
	s_addc_u32 s73, s57, 0
	v_readlane_b32 s50, v252, 37
	v_readlane_b32 s51, v252, 38
	s_add_u32 s74, s50, s2
	s_addc_u32 s75, s51, s3
	s_add_u32 s76, s56, s68
	s_addc_u32 s77, s57, 0
	s_add_u32 s78, s50, s4
	v_mov_b32_e32 v3, s90
	v_cmp_gt_i32_e32 vcc, 32, v1
	s_mul_hi_u32 s8, s16, 0x2420000
	v_writelane_b32 v255, s16, 32
	s_mul_i32 s9, s16, 0x2420000
	s_addc_u32 s79, s51, s5
	v_cndmask_b32_e32 v161, v2, v3, vcc
	s_add_u32 s80, s38, s9
	s_mov_b32 s67, s69
	v_writelane_b32 v255, s17, 33
	s_addc_u32 s81, s39, s8
	v_lshlrev_b32_e32 v162, 3, v1
	v_lshlrev_b32_e32 v163, 3, v161
	v_lshlrev_b32_e32 v164, 10, v1
	v_lshlrev_b32_e32 v165, 10, v161
	v_lshrrev_b32_e32 v162, 1, v181
	v_and_b32_e32 v163, 1, v181
	v_add_u32_e32 v1, 0x68, v181
	v_mov_b32_e32 v161, 0x1c0
	v_add_u32_e32 v215, 32, v162
	v_cmp_eq_u32_e32 vcc, 1, v163
	v_cndmask_b32_e32 v215, v162, v215, vcc
	v_mov_b32_e32 v165, s90
	v_mov_b32_e32 v164, 32
	v_cndmask_b32_e32 v165, v165, v164, vcc
	v_cmp_gt_u32_e32 vcc, 32, v162
	v_cndmask_b32_e32 v1, v1, v215, vcc
	v_cndmask_b32_e32 v161, v161, v165, vcc
	v_lshlrev_b32_e32 v164, 10, v1
	v_mov_b32_e32 v163, 0
	s_nop 1
	v_readfirstlane_b32 s36, v180
	v_readfirstlane_b32 s37, v161
	s_nop 1
	s_cmp_lt_u32 s36, 64
	s_cbranch_scc0 .Lm2_pre_done
	s_cmp_eq_u32 s37, 0x1c0
	s_cbranch_scc0 .Lm2_pre_done
	v_readlane_b32 s38, v252, 7
	v_readlane_b32 s39, v252, 8
	s_lshl_b32 s40, s92, 3
	s_add_u32 s40, s40, 0x2194e100
	s_nop 1
	s_add_u32 s38, s38, s40
	s_addc_u32 s39, s39, 0
	s_mov_b64 s[42:43], exec
	s_mov_b64 exec, 1
	v_mov_b32_e32 v215, 2
	s_nop 1
	global_atomic_add v162, v0, v215, s[38:39] sc0
	s_mov_b64 exec, s[42:43]
.Lm2_pre_done:
	s_mov_b64 s[82:83], 0
	v_readlane_b32 s37, v252, 12
	v_readlane_b32 s58, v252, 53
	v_readlane_b32 s59, v252, 54
	v_readlane_b32 s60, v252, 55
	v_readlane_b32 s61, v252, 56
	v_readlane_b32 s62, v252, 57
	v_readlane_b32 s63, v252, 58
	v_readlane_b32 s41, v252, 28
	v_readlane_b32 s42, v252, 29
	v_readlane_b32 s43, v252, 30
	v_readlane_b32 s44, v252, 31
	v_readlane_b32 s45, v252, 32
	v_readlane_b32 s46, v252, 33
	v_readlane_b32 s47, v252, 34
	v_readlane_b32 s48, v252, 35
	v_readlane_b32 s49, v252, 36
	v_readlane_b32 s52, v252, 39
	v_readlane_b32 s53, v252, 40
	v_readlane_b32 s54, v252, 41
	v_readlane_b32 s55, v252, 42
	s_branch .LBB0_897

; DI void phase_m2(const Params& p, int l, int bid, int nb, h16* lds) {
;     ...
;   for (int u = ustart; u < total; u += ustep) {
.LBB0_896:
	s_or_b64 exec, exec, s[4:5]
	v_readfirstlane_b32 s36, v161
	v_readfirstlane_b32 s37, v163
	s_nop 1
	s_cmp_eq_u32 s36, 0x1c0
	s_cbranch_scc0 .Lm2_static
	s_cmp_eq_u32 s37, 0
	s_cbranch_scc0 .Lm2_static
	s_barrier
	v_readfirstlane_b32 s37, v180
	s_nop 1
	s_cmp_lt_u32 s37, 64
	s_cbranch_scc0 .Lm2_nofetch
	s_waitcnt vmcnt(0)
	s_mov_b64 s[42:43], exec
	s_mov_b64 exec, 1
	s_nop 1
	ds_write_b32 v0, v162 offset:12
	v_readlane_b32 s38, v252, 7
	v_readlane_b32 s39, v252, 8
	s_lshl_b32 s40, s92, 3
	s_add_u32 s40, s40, 0x2194e100
	s_nop 1
	s_add_u32 s38, s38, s40
	s_addc_u32 s39, s39, 0
	v_mov_b32_e32 v215, 2
	s_waitcnt lgkmcnt(0)
	global_atomic_add v162, v0, v215, s[38:39] sc0
	s_mov_b64 exec, s[42:43]
.Lm2_nofetch:
	s_barrier
	ds_read_b32 v215, v0 offset:12
	s_waitcnt lgkmcnt(0)
	v_add_u32_e32 v215, 0x268, v215
	s_nop 3
	v_readfirstlane_b32 s36, v215
	s_nop 3
	s_cmp_lt_u32 s36, 0x14a8
	s_cbranch_scc1 .Lm2_dyn_ok
	v_mov_b32_e32 v163, 1
	v_add_u32_e32 v1, 0x1468, v181
	s_branch .Lm2_stepped
.Lm2_dyn_ok:
	v_and_b32_e32 v1, 1, v181
	v_add_u32_e32 v1, v1, v215
	s_branch .Lm2_stepped
.Lm2_static:
	v_add_u32_e32 v1, v1, v161
	v_mov_b32_e32 v215, s90
	v_cmp_le_u32_e32 vcc, 0xa8, v1
	s_mov_b64 s[36:37], vcc
	v_cmp_eq_u32_e32 vcc, 32, v161
	s_and_b64 vcc, vcc, s[36:37]
	v_cndmask_b32_e32 v1, v1, v215, vcc
.Lm2_stepped:
	v_cmp_le_i32_e32 vcc, s90, v1
	s_or_b64 s[82:83], vcc, s[82:83]
	s_andn2_b64 exec, exec, s[82:83]
	s_cbranch_execz .LBB0_1028
